# half 2: the 7 leading p1 exps moved ahead of the first K-read wait (hidden under LDS latency)
# baseline (speedup 1.0000x reference)
; #define SBAR() __builtin_amdgcn_sched_barrier(0)
; #define PK4(P, BASE, OUT) do { u32x4 w = {cvtpk(P[BASE + 0], P[BASE + 1]), cvtpk(P[BASE + 2], P[BASE + 3]), cvtpk(P[BASE + 4], P[BASE + 5]), cvtpk(P[BASE + 6], P[BASE + 7])}; \
;     OUT = *reinterpret_cast<bf16x8*>(&w); } while (0)
; #define PUBLISH(n) do { asm volatile("s_waitcnt vmcnt(" #n ")" ::: "memory"); asm volatile("s_waitcnt lgkmcnt(0)" ::: "memory"); __builtin_amdgcn_s_barrier(); SBAR(); } while (0)
; __device__ __forceinline__ void finishSM(f32x16& p0, f32x16& p1, float alpha, float& l_reg, bf16x8& pa0, bf16x8& pa1, bf16x8& pa2, bf16x8& pa3) {
;   for (int r = 0; r < 16; ++r) p1[r] = __builtin_amdgcn_exp2f(p1[r]);
;   float ps = 0; for (int r = 0; r < 16; ++r) ps += p0[r]; for (int r = 0; r < 16; ++r) ps += p1[r];
;   asm volatile("" : "+v"(ps));
;   l_reg = l_reg * alpha + ps;
;     ...
;   PK4(p0, 0, pa0); PK4(p0, 8, pa1); PK4(p1, 0, pa2); PK4(p1, 8, pa3);
;     ...
; }
; __device__ __forceinline__ void qkt(f32x16& p0, f32x16& p1, const bf16* Ks, const bf16x8* qr, int r32, int hi) {
;   p0 = f32x16{}; p1 = f32x16{};
;   for (int d0 = 0; d0 < 8; ++d0) { int cb = (d0 * 16 + hi * 8) * 2;
;     bf16x8 b0 = *reinterpret_cast<const bf16x8*>((const char*)Ks + KSWZ(r32, cb));
;     bf16x8 b1 = *reinterpret_cast<const bf16x8*>((const char*)Ks + KSWZ(32 + r32, cb));
;     p0 = __builtin_amdgcn_mfma_f32_32x32x16_bf16(b0, qr[d0], p0, 0, 0, 0);
;     p1 = __builtin_amdgcn_mfma_f32_32x32x16_bf16(b1, qr[d0], p1, 0, 0, 0); }
; }
; template <typename TQ> ...
;     ...
;   for (int j = 1; j + 1 < NT; j += 2) {
;     SBAR(); qkt(pB0, pB1, (const bf16*)(K_lds + (j & 3) * (int)SHM_K), qr, r32, hi);
;     finishSM(pA0, pA1, alA, l_reg, pa0, pa1, pa2, pa3); SBAR();
;     DMA_TILE(j + 2, (j + 2) & 3); SBAR();
;     pv_d0(o, vb0 + ((j - 1) & 3) * (int)SHM_V, pa0, pa1, pa2, pa3); partialSM<true>(pB0, pB1, m_reg, mnB, alB);
;     PUBLISH(4);
;     SBAR(); qkt(pA0, pA1, (const bf16*)(K_lds + ((j + 1) & 3) * (int)SHM_K), qr, r32, hi);
;     finishSM(pB0, pB1, alB, l_reg, pa0, pa1, pa2, pa3); SBAR();
;     if (j + 3 < NT) { DMA_TILE(j + 3, (j + 3) & 3); } SBAR();
;     pv_d0(o, vb0 + (j & 3) * (int)SHM_V, pa0, pa1, pa2, pa3); partialSM<true>(pA0, pA1, m_reg, mnA, alA);
.Lat461_a_go:
	s_waitcnt lgkmcnt(3)
	v_mfma_f32_32x32x16_bf16 v[96:111], v[80:83], v[136:139], 0
	v_exp_f32_e32 v238, v64
	v_add_f32_e32 v64, v197, v196
	v_add_f32_e32 v64, v193, v64
	v_add_f32_e32 v64, v195, v64
	s_waitcnt lgkmcnt(2)
	v_mfma_f32_32x32x16_bf16 v[80:95], v[84:87], v[136:139], 0
	v_add_f32_e32 v64, v191, v64
	v_add_f32_e32 v64, v194, v64
	v_add_f32_e32 v64, v190, v64
	v_add_f32_e32 v64, v192, v64
	v_add_f32_e32 v64, v169, v64
	v_add_f32_e32 v64, v171, v64
	s_waitcnt lgkmcnt(1)
	v_mfma_f32_32x32x16_bf16 v[96:111], v[198:201], v[140:143], v[96:111]
	v_add_f32_e32 v64, v167, v64
	v_add_f32_e32 v64, v170, v64
	v_add_f32_e32 v64, v165, v64
	v_add_f32_e32 v64, v168, v64
	v_add_f32_e32 v64, v164, v64
	v_add_f32_e32 v64, v166, v64
	v_exp_f32_e32 v239, v68
	s_waitcnt lgkmcnt(0)
	v_mfma_f32_32x32x16_bf16 v[80:95], v[202:205], v[140:143], v[80:95]
	ds_read_b128 v[198:201], v180 offset:16384
	ds_read_b128 v[202:205], v180 offset:24576
	v_add_f32_e32 v64, v238, v64
	v_exp_f32_e32 v240, v69
	v_exp_f32_e32 v241, v70
	v_exp_f32_e32 v242, v71
	s_waitcnt lgkmcnt(1)
	v_mfma_f32_32x32x16_bf16 v[96:111], v[198:201], v[132:135], v[96:111]
	ds_read_b128 v[198:201], v181 offset:16384
	ds_read_b128 v[206:209], v181 offset:24576
	ds_read_b128 v[210:213], v182 offset:16384
	ds_read_b128 v[214:217], v182 offset:24576
	ds_read_b128 v[218:221], v183 offset:16384
	ds_read_b128 v[222:225], v183 offset:24576
	v_exp_f32_e32 v243, v76
	v_exp_f32_e32 v244, v77
	v_exp_f32_e32 v245, v78
	v_exp_f32_e32 v79, v79
	s_waitcnt lgkmcnt(6)
	v_mfma_f32_32x32x16_bf16 v[80:95], v[202:205], v[132:135], v[80:95]
	ds_read_b128 v[202:205], v184 offset:16384
	ds_read_b128 v[226:229], v184 offset:24576
	ds_read_b128 v[230:233], v185 offset:16384
	ds_read_b128 v[234:237], v185 offset:24576
	s_waitcnt lgkmcnt(9)
	v_mfma_f32_32x32x16_bf16 v[96:111], v[198:201], v[128:131], v[96:111]
	v_exp_f32_e32 v199, v65
	v_exp_f32_e32 v200, v66
	v_exp_f32_e32 v201, v67
	v_add_f32_e32 v64, v199, v64
	v_add_f32_e32 v64, v200, v64
	v_add_f32_e32 v64, v201, v64
	s_waitcnt lgkmcnt(8)
	v_mfma_f32_32x32x16_bf16 v[80:95], v[206:209], v[128:131], v[80:95]
	v_exp_f32_e32 v206, v72
	v_add_f32_e32 v64, v239, v64
	v_exp_f32_e32 v207, v73
	v_add_f32_e32 v64, v240, v64
	v_exp_f32_e32 v208, v74
	v_add_f32_e32 v64, v241, v64
	v_exp_f32_e32 v209, v75
	s_waitcnt lgkmcnt(7)
	v_mfma_f32_32x32x16_bf16 v[96:111], v[210:213], v[124:127], v[96:111]
	v_add_f32_e32 v64, v242, v64
	v_add_f32_e32 v64, v206, v64
	v_add_f32_e32 v64, v207, v64
	v_add_f32_e32 v64, v208, v64
	v_add_f32_e32 v64, v209, v64
	v_add_f32_e32 v64, v243, v64
	v_add_f32_e32 v64, v244, v64
	s_waitcnt lgkmcnt(6)
	v_mfma_f32_32x32x16_bf16 v[80:95], v[214:217], v[124:127], v[80:95]
	v_add_f32_e32 v64, v245, v64
	v_add_f32_e32 v198, v79, v64
	v_cvt_pk_bf16_f32 v64, v196, v197
	v_cvt_pk_bf16_f32 v65, v193, v195
	v_cvt_pk_bf16_f32 v66, v191, v194
	v_cvt_pk_bf16_f32 v67, v190, v192
	s_waitcnt lgkmcnt(5)
	v_mfma_f32_32x32x16_bf16 v[96:111], v[218:221], v[120:123], v[96:111]
	v_cvt_pk_bf16_f32 v68, v169, v171
	v_cvt_pk_bf16_f32 v69, v167, v170
	v_cvt_pk_bf16_f32 v70, v165, v168
	v_cvt_pk_bf16_f32 v71, v164, v166
	v_cvt_pk_bf16_f32 v72, v238, v199
	v_cvt_pk_bf16_f32 v73, v200, v201
	v_cvt_pk_bf16_f32 v74, v239, v240
	s_waitcnt lgkmcnt(4)
	v_mfma_f32_32x32x16_bf16 v[80:95], v[222:225], v[120:123], v[80:95]
	v_cvt_pk_bf16_f32 v75, v241, v242
	v_cvt_pk_bf16_f32 v76, v206, v207
	v_cvt_pk_bf16_f32 v77, v208, v209
	v_cvt_pk_bf16_f32 v78, v243, v244
	v_cvt_pk_bf16_f32 v79, v245, v79
	s_waitcnt lgkmcnt(3)
	v_mfma_f32_32x32x16_bf16 v[96:111], v[202:205], v[116:119], v[96:111]
	s_add_i32 s33, s40, 0x8000
	s_and_b32 s43, s33, 0xc000
	ds_read_b64_tr_b16 v[190:191], v176
	ds_read_b64_tr_b16 v[192:193], v176 offset:2048
	ds_read_b64_tr_b16 v[194:195], v176 offset:4096
	ds_read_b64_tr_b16 v[196:197], v176 offset:6144
	s_waitcnt lgkmcnt(6)
	v_mfma_f32_32x32x16_bf16 v[80:95], v[226:229], v[116:119], v[80:95]
	ds_read_b64_tr_b16 v[200:201], v176 offset:8192
	ds_read_b64_tr_b16 v[202:203], v176 offset:10240
	ds_read_b64_tr_b16 v[204:205], v176 offset:12288
	ds_read_b64_tr_b16 v[206:207], v176 offset:14336
	s_add_i32 s74, s40, 0x4000
	s_and_b32 s74, s74, 0xc000
	s_add_u32 s98, s38, s22
	s_addc_u32 s99, s39, s23
	s_add_i32 s41, s67, s74
	s_add_u32 s100, s38, s24
	s_addc_u32 s101, s39, s25
	s_mov_b32 m0, s41
	s_add_i32 s74, s72, s74
	global_load_lds_dwordx4 v156, s[98:99]
	s_waitcnt lgkmcnt(9)
	v_mfma_f32_32x32x16_bf16 v[96:111], v[230:233], v[112:115], v[96:111]
	s_add_i32 m0, s41, 0x2000
	s_nop 0
	global_load_lds_dwordx4 v158, s[98:99]
	s_mov_b32 m0, s74
	s_nop 0
	global_load_lds_dwordx4 v162, s[100:101]
	s_waitcnt lgkmcnt(8)
	v_mfma_f32_32x32x16_bf16 v[80:95], v[234:237], v[112:115], v[80:95]
	s_add_i32 m0, s74, 0x2000
	s_nop 0
	global_load_lds_dwordx4 v160, s[100:101]
	s_nop 0
	s_waitcnt lgkmcnt(6)
	v_mfma_f32_32x32x16_bf16 v[48:63], v[64:67], v[190:193], v[48:63]
	v_exp_f32_e32 v232, v96
	ds_read_b64_tr_b16 v[190:191], v176 offset:512
	ds_read_b64_tr_b16 v[192:193], v176 offset:2560
	s_waitcnt lgkmcnt(6)
; #define SBAR() __builtin_amdgcn_sched_barrier(0)
; #define PUBLISH(n) do { asm volatile("s_waitcnt vmcnt(" #n ")" ::: "memory"); asm volatile("s_waitcnt lgkmcnt(0)" ::: "memory"); __builtin_amdgcn_s_barrier(); SBAR(); } while (0)
; template <int D0> __device__ __forceinline__ void pv_one(f32x16& od, int vb, bf16x8 pa0, bf16x8 pa1, bf16x8 pa2, bf16x8 pa3) {
;   const s16x4 l0 = tr_read<v_rd_off(D0, 0, 0)>(vb), h0 = tr_read<v_rd_off(D0, 0, 1)>(vb), l1 = tr_read<v_rd_off(D0, 1, 0)>(vb), h1 = tr_read<v_rd_off(D0, 1, 1)>(vb);
;   const s16x4 l2 = tr_read<v_rd_off(D0, 2, 0)>(vb), h2 = tr_read<v_rd_off(D0, 2, 1)>(vb), l3 = tr_read<v_rd_off(D0, 3, 0)>(vb), h3 = tr_read<v_rd_off(D0, 3, 1)>(vb);
;   asm volatile("s_waitcnt lgkmcnt(0)" ::: "memory"); SBAR();
;     ...
;   od = __builtin_amdgcn_mfma_f32_32x32x16_bf16(pa0, PK(l0, h0), od, 0, 0, 0);
;   od = __builtin_amdgcn_mfma_f32_32x32x16_bf16(pa1, PK(l1, h1), od, 0, 0, 0);
;   od = __builtin_amdgcn_mfma_f32_32x32x16_bf16(pa2, PK(l2, h2), od, 0, 0, 0);
;   od = __builtin_amdgcn_mfma_f32_32x32x16_bf16(pa3, PK(l3, h3), od, 0, 0, 0);
;     ...
; }
; __device__ __forceinline__ void pv_d0(f32x16* o, int vb, bf16x8 pa0, bf16x8 pa1, bf16x8 pa2, bf16x8 pa3) {
;   pv_one<0>(o[0], vb, pa0, pa1, pa2, pa3); pv_one<1>(o[1], vb, pa0, pa1, pa2, pa3); pv_one<2>(o[2], vb, pa0, pa1, pa2, pa3); pv_one<3>(o[3], vb, pa0, pa1, pa2, pa3);
; }
; template <typename TQ> ...
;     ...
;   for (int j = 1; j + 1 < NT; j += 2) {
;     SBAR(); qkt(pB0, pB1, (const bf16*)(K_lds + (j & 3) * (int)SHM_K), qr, r32, hi);
;     finishSM(pA0, pA1, alA, l_reg, pa0, pa1, pa2, pa3); SBAR();
;     DMA_TILE(j + 2, (j + 2) & 3); SBAR();
;     pv_d0(o, vb0 + ((j - 1) & 3) * (int)SHM_V, pa0, pa1, pa2, pa3); partialSM<true>(pB0, pB1, m_reg, mnB, alB);
;     PUBLISH(4);
;     SBAR(); qkt(pA0, pA1, (const bf16*)(K_lds + ((j + 1) & 3) * (int)SHM_K), qr, r32, hi);
	v_mfma_f32_32x32x16_bf16 v[48:63], v[68:71], v[194:197], v[48:63]
	v_exp_f32_e32 v233, v97
	ds_read_b64_tr_b16 v[194:195], v176 offset:4608
	ds_read_b64_tr_b16 v[196:197], v176 offset:6656
	s_waitcnt lgkmcnt(6)
	v_mfma_f32_32x32x16_bf16 v[48:63], v[72:75], v[200:203], v[48:63]
	v_exp_f32_e32 v234, v98
	ds_read_b64_tr_b16 v[200:201], v176 offset:8704
	ds_read_b64_tr_b16 v[202:203], v176 offset:10752
	ds_read_b64_tr_b16 v[208:209], v176 offset:12800
	ds_read_b64_tr_b16 v[210:211], v176 offset:14848
	s_waitcnt lgkmcnt(8)
	v_mfma_f32_32x32x16_bf16 v[48:63], v[76:79], v[204:207], v[48:63]
	v_exp_f32_e32 v235, v99
	s_waitcnt lgkmcnt(6)
	v_mfma_f32_32x32x16_bf16 v[32:47], v[64:67], v[190:193], v[32:47]
	v_exp_f32_e32 v236, v100
	ds_read_b64_tr_b16 v[190:191], v176 offset:1024
	ds_read_b64_tr_b16 v[192:193], v176 offset:3072
	s_waitcnt lgkmcnt(6)
	v_mfma_f32_32x32x16_bf16 v[32:47], v[68:71], v[194:197], v[32:47]
	v_exp_f32_e32 v237, v101
	ds_read_b64_tr_b16 v[194:195], v176 offset:5120
	ds_read_b64_tr_b16 v[196:197], v176 offset:7168
	s_waitcnt lgkmcnt(6)
	v_mfma_f32_32x32x16_bf16 v[32:47], v[72:75], v[200:203], v[32:47]
	v_exp_f32_e32 v238, v102
	ds_read_b64_tr_b16 v[200:201], v176 offset:9216
	ds_read_b64_tr_b16 v[202:203], v176 offset:11264
	ds_read_b64_tr_b16 v[204:205], v176 offset:13312
	ds_read_b64_tr_b16 v[206:207], v176 offset:15360
	s_waitcnt lgkmcnt(8)
	v_mfma_f32_32x32x16_bf16 v[32:47], v[76:79], v[208:211], v[32:47]
	v_exp_f32_e32 v239, v103
	v_exp_f32_e32 v240, v104
	s_waitcnt lgkmcnt(6)
	v_mfma_f32_32x32x16_bf16 v[16:31], v[64:67], v[190:193], v[16:31]
	v_exp_f32_e32 v241, v105
	ds_read_b64_tr_b16 v[190:191], v176 offset:1536
	ds_read_b64_tr_b16 v[192:193], v176 offset:3584
	s_waitcnt lgkmcnt(6)
	v_mfma_f32_32x32x16_bf16 v[16:31], v[68:71], v[194:197], v[16:31]
	v_exp_f32_e32 v242, v106
	ds_read_b64_tr_b16 v[194:195], v176 offset:5632
	ds_read_b64_tr_b16 v[196:197], v176 offset:7680
	s_waitcnt lgkmcnt(6)
	v_mfma_f32_32x32x16_bf16 v[16:31], v[72:75], v[200:203], v[16:31]
	v_exp_f32_e32 v243, v107
	ds_read_b64_tr_b16 v[200:201], v176 offset:9728
	ds_read_b64_tr_b16 v[202:203], v176 offset:11776
	ds_read_b64_tr_b16 v[208:209], v176 offset:13824
	ds_read_b64_tr_b16 v[210:211], v176 offset:15872
	s_waitcnt lgkmcnt(8)
	v_mfma_f32_32x32x16_bf16 v[16:31], v[76:79], v[204:207], v[16:31]
	v_exp_f32_e32 v244, v108
	s_waitcnt lgkmcnt(6)
	v_mfma_f32_32x32x16_bf16 v[0:15], v[64:67], v[190:193], v[0:15]
	v_exp_f32_e32 v245, v109
	s_waitcnt lgkmcnt(4)
	v_mfma_f32_32x32x16_bf16 v[0:15], v[68:71], v[194:197], v[0:15]
	v_exp_f32_e32 v246, v110
	s_waitcnt lgkmcnt(2)
	v_mfma_f32_32x32x16_bf16 v[0:15], v[72:75], v[200:203], v[0:15]
	v_exp_f32_e32 v247, v111
	s_waitcnt vmcnt(4)
	s_waitcnt lgkmcnt(0)
	s_barrier
	v_mfma_f32_32x32x16_bf16 v[0:15], v[76:79], v[208:211], v[0:15]
	s_and_b32 s40, s40, 0xc000
	s_add_i32 s40, s57, s40
	ds_read_b128 v[64:67], v178 offset:32768
	ds_read_b128 v[68:71], v178 offset:40960
	ds_read_b128 v[190:193], v179 offset:32768
	ds_read_b128 v[194:197], v179 offset:40960
	v_exp_f32_e32 v80, v80
	v_exp_f32_e32 v81, v81
	v_exp_f32_e32 v82, v82
	v_exp_f32_e32 v83, v83
	v_exp_f32_e32 v87, v87
	v_exp_f32_e32 v248, v93
	v_exp_f32_e32 v249, v94
	s_waitcnt lgkmcnt(3)
	v_mfma_f32_32x32x16_bf16 v[96:111], v[64:67], v[136:139], 0
	s_waitcnt lgkmcnt(2)
	v_mfma_f32_32x32x16_bf16 v[64:79], v[68:71], v[136:139], 0
	s_waitcnt lgkmcnt(1)
	v_mfma_f32_32x32x16_bf16 v[96:111], v[190:193], v[140:143], v[96:111]
	s_waitcnt lgkmcnt(0)
	v_mfma_f32_32x32x16_bf16 v[64:79], v[194:197], v[140:143], v[64:79]
	ds_read_b128 v[190:193], v180 offset:32768
	ds_read_b128 v[194:197], v180 offset:40960
	s_waitcnt lgkmcnt(1)
	v_mfma_f32_32x32x16_bf16 v[96:111], v[190:193], v[132:135], v[96:111]
	ds_read_b128 v[190:193], v181 offset:32768
	ds_read_b128 v[200:203], v181 offset:40960
	ds_read_b128 v[204:207], v182 offset:32768
	ds_read_b128 v[208:211], v182 offset:40960
	ds_read_b128 v[212:215], v183 offset:32768
	ds_read_b128 v[216:219], v183 offset:40960
	s_waitcnt lgkmcnt(6)
	v_mfma_f32_32x32x16_bf16 v[64:79], v[194:197], v[132:135], v[64:79]
	ds_read_b128 v[194:197], v184 offset:32768
	ds_read_b128 v[220:223], v184 offset:40960
	ds_read_b128 v[224:227], v185 offset:32768
	ds_read_b128 v[228:231], v185 offset:40960
	s_waitcnt lgkmcnt(9)
	v_mfma_f32_32x32x16_bf16 v[96:111], v[190:193], v[128:131], v[96:111]
	s_cmp_ge_u32 s73, s37
	s_cselect_b64 s[40:41], -1, 0
	s_and_b64 vcc, exec, s[40:41]
	s_cbranch_vccnz .LBB0_463
	s_add_i32 s74, s67, s43
	s_add_u32 s98, s38, s26
	s_addc_u32 s99, s39, s27
	s_mov_b32 m0, s74
	s_add_i32 s43, s72, s43
	global_load_lds_dwordx4 v156, s[98:99]
	s_add_u32 s100, s38, s28
	s_addc_u32 s101, s39, s29
	s_add_i32 m0, s74, 0x2000
	s_nop 0
	global_load_lds_dwordx4 v158, s[98:99]
	s_mov_b32 m0, s43
	s_nop 0
	global_load_lds_dwordx4 v162, s[100:101]
	s_add_i32 m0, s43, 0x2000
	s_nop 0
	global_load_lds_dwordx4 v160, s[100:101]

; #define SBAR() __builtin_amdgcn_sched_barrier(0)
; #define PK4(P, BASE, OUT) do { u32x4 w = {cvtpk(P[BASE + 0], P[BASE + 1]), cvtpk(P[BASE + 2], P[BASE + 3]), cvtpk(P[BASE + 4], P[BASE + 5]), cvtpk(P[BASE + 6], P[BASE + 7])}; \
;     OUT = *reinterpret_cast<bf16x8*>(&w); } while (0)
; __device__ __forceinline__ void finishSM(f32x16& p0, f32x16& p1, float alpha, float& l_reg, bf16x8& pa0, bf16x8& pa1, bf16x8& pa2, bf16x8& pa3) {
;   for (int r = 0; r < 16; ++r) p1[r] = __builtin_amdgcn_exp2f(p1[r]);
;   float ps = 0; for (int r = 0; r < 16; ++r) ps += p0[r]; for (int r = 0; r < 16; ++r) ps += p1[r];
;   asm volatile("" : "+v"(ps));
;   l_reg = l_reg * alpha + ps;
;     ...
;   PK4(p0, 0, pa0); PK4(p0, 8, pa1); PK4(p1, 0, pa2); PK4(p1, 8, pa3);
;     ...
; }
; __device__ __forceinline__ void qkt(f32x16& p0, f32x16& p1, const bf16* Ks, const bf16x8* qr, int r32, int hi) {
;   p0 = f32x16{}; p1 = f32x16{};
;   for (int d0 = 0; d0 < 8; ++d0) { int cb = (d0 * 16 + hi * 8) * 2;
;     bf16x8 b0 = *reinterpret_cast<const bf16x8*>((const char*)Ks + KSWZ(r32, cb));
;     bf16x8 b1 = *reinterpret_cast<const bf16x8*>((const char*)Ks + KSWZ(32 + r32, cb));
;     p0 = __builtin_amdgcn_mfma_f32_32x32x16_bf16(b0, qr[d0], p0, 0, 0, 0);
;     p1 = __builtin_amdgcn_mfma_f32_32x32x16_bf16(b1, qr[d0], p1, 0, 0, 0); }
; }
; template <typename TQ> ...
;     ...
;     SBAR(); qkt(pA0, pA1, (const bf16*)(K_lds + ((j + 1) & 3) * (int)SHM_K), qr, r32, hi);
;     finishSM(pB0, pB1, alB, l_reg, pa0, pa1, pa2, pa3); SBAR();
;     if (j + 3 < NT) { DMA_TILE(j + 3, (j + 3) & 3); } SBAR();
;     pv_d0(o, vb0 + (j & 3) * (int)SHM_V, pa0, pa1, pa2, pa3); partialSM<true>(pA0, pA1, m_reg, mnA, alA);
.Lat461_b:
.Lat461_b_in:
	s_mov_b32 s40, s33
	s_addk_i32 s33, 0xc000
	s_and_b32 s42, s33, 0xc000
	s_add_i32 s33, s57, s42
	ds_read_b128 v[80:83], v178 offset:49152
	ds_read_b128 v[84:87], v178 offset:57344
	ds_read_b128 v[198:201], v179 offset:49152
	ds_read_b128 v[202:205], v179 offset:57344
	v_exp_f32_e32 v196, v96
	v_exp_f32_e32 v197, v97
	v_exp_f32_e32 v193, v98
	v_exp_f32_e32 v195, v99
	v_exp_f32_e32 v191, v100
	v_exp_f32_e32 v194, v101
	v_exp_f32_e32 v190, v102
	v_exp_f32_e32 v192, v103
	v_exp_f32_e32 v169, v104
	v_exp_f32_e32 v171, v105
	v_exp_f32_e32 v167, v106
	v_exp_f32_e32 v170, v107
	v_exp_f32_e32 v165, v108
	v_exp_f32_e32 v168, v109
	v_exp_f32_e32 v164, v110
	v_exp_f32_e32 v166, v111
	s_waitcnt lgkmcnt(3)
	v_mfma_f32_32x32x16_bf16 v[96:111], v[80:83], v[136:139], 0
	v_exp_f32_e32 v238, v64
	v_add_f32_e32 v64, v197, v196
	v_add_f32_e32 v64, v193, v64
	v_add_f32_e32 v64, v195, v64
	s_waitcnt lgkmcnt(2)
	v_mfma_f32_32x32x16_bf16 v[80:95], v[84:87], v[136:139], 0
	v_add_f32_e32 v64, v191, v64
	v_add_f32_e32 v64, v194, v64
	v_add_f32_e32 v64, v190, v64
	v_add_f32_e32 v64, v192, v64
	v_add_f32_e32 v64, v169, v64
	v_add_f32_e32 v64, v171, v64
	s_waitcnt lgkmcnt(1)
	v_mfma_f32_32x32x16_bf16 v[96:111], v[198:201], v[140:143], v[96:111]
	v_add_f32_e32 v64, v167, v64
	v_add_f32_e32 v64, v170, v64
	v_add_f32_e32 v64, v165, v64
	v_add_f32_e32 v64, v168, v64
	v_add_f32_e32 v64, v164, v64
	v_add_f32_e32 v64, v166, v64
	v_exp_f32_e32 v239, v68
	s_waitcnt lgkmcnt(0)
	v_mfma_f32_32x32x16_bf16 v[80:95], v[202:205], v[140:143], v[80:95]
	ds_read_b128 v[198:201], v180 offset:49152
	ds_read_b128 v[202:205], v180 offset:57344
	v_add_f32_e32 v64, v238, v64
	v_exp_f32_e32 v240, v69
	v_exp_f32_e32 v241, v70
	v_exp_f32_e32 v242, v71
	s_waitcnt lgkmcnt(1)
	v_mfma_f32_32x32x16_bf16 v[96:111], v[198:201], v[132:135], v[96:111]
	ds_read_b128 v[198:201], v181 offset:49152
	ds_read_b128 v[206:209], v181 offset:57344
	ds_read_b128 v[210:213], v182 offset:49152
	ds_read_b128 v[214:217], v182 offset:57344
	ds_read_b128 v[218:221], v183 offset:49152
	ds_read_b128 v[222:225], v183 offset:57344
	v_exp_f32_e32 v243, v76
	v_exp_f32_e32 v244, v77
	v_exp_f32_e32 v245, v78
	v_exp_f32_e32 v79, v79
	s_waitcnt lgkmcnt(6)
	v_mfma_f32_32x32x16_bf16 v[80:95], v[202:205], v[132:135], v[80:95]
	ds_read_b128 v[202:205], v184 offset:49152
	ds_read_b128 v[226:229], v184 offset:57344
	ds_read_b128 v[230:233], v185 offset:49152
	ds_read_b128 v[234:237], v185 offset:57344
	s_waitcnt lgkmcnt(9)
	v_mfma_f32_32x32x16_bf16 v[96:111], v[198:201], v[128:131], v[96:111]
	v_exp_f32_e32 v199, v65
	v_exp_f32_e32 v200, v66
	v_exp_f32_e32 v201, v67
	v_add_f32_e32 v64, v199, v64
	v_add_f32_e32 v64, v200, v64
	v_add_f32_e32 v64, v201, v64
	s_waitcnt lgkmcnt(8)
	v_mfma_f32_32x32x16_bf16 v[80:95], v[206:209], v[128:131], v[80:95]
	v_exp_f32_e32 v206, v72
	v_add_f32_e32 v64, v239, v64
	v_exp_f32_e32 v207, v73
	v_add_f32_e32 v64, v240, v64
	v_exp_f32_e32 v208, v74
	v_add_f32_e32 v64, v241, v64
	v_exp_f32_e32 v209, v75
	s_waitcnt lgkmcnt(7)
	v_mfma_f32_32x32x16_bf16 v[96:111], v[210:213], v[124:127], v[96:111]
	v_add_f32_e32 v64, v242, v64
	v_add_f32_e32 v64, v206, v64
	v_add_f32_e32 v64, v207, v64
	v_add_f32_e32 v64, v208, v64
	v_add_f32_e32 v64, v209, v64
	v_add_f32_e32 v64, v243, v64
	v_add_f32_e32 v64, v244, v64
	s_waitcnt lgkmcnt(6)
	v_mfma_f32_32x32x16_bf16 v[80:95], v[214:217], v[124:127], v[80:95]
	v_add_f32_e32 v64, v245, v64
	v_add_f32_e32 v198, v79, v64
	v_cvt_pk_bf16_f32 v64, v196, v197
	v_cvt_pk_bf16_f32 v65, v193, v195
	v_cvt_pk_bf16_f32 v66, v191, v194
	v_cvt_pk_bf16_f32 v67, v190, v192
	s_waitcnt lgkmcnt(5)
	v_mfma_f32_32x32x16_bf16 v[96:111], v[218:221], v[120:123], v[96:111]
	v_cvt_pk_bf16_f32 v68, v169, v171
	v_cvt_pk_bf16_f32 v69, v167, v170
	v_cvt_pk_bf16_f32 v70, v165, v168
	v_cvt_pk_bf16_f32 v71, v164, v166
	v_cvt_pk_bf16_f32 v72, v238, v199
	v_cvt_pk_bf16_f32 v73, v200, v201
	v_cvt_pk_bf16_f32 v74, v239, v240
	s_waitcnt lgkmcnt(4)
	v_mfma_f32_32x32x16_bf16 v[80:95], v[222:225], v[120:123], v[80:95]
	v_cvt_pk_bf16_f32 v75, v241, v242
	v_cvt_pk_bf16_f32 v76, v206, v207
	v_cvt_pk_bf16_f32 v77, v208, v209
	v_cvt_pk_bf16_f32 v78, v243, v244
	v_cvt_pk_bf16_f32 v79, v245, v79
	s_waitcnt lgkmcnt(3)
	v_mfma_f32_32x32x16_bf16 v[96:111], v[202:205], v[116:119], v[96:111]
	s_add_i32 s33, s40, 0x8000
	s_and_b32 s43, s33, 0xc000
	ds_read_b64_tr_b16 v[190:191], v176 offset:32768
	ds_read_b64_tr_b16 v[192:193], v176 offset:34816
	ds_read_b64_tr_b16 v[194:195], v176 offset:36864
	ds_read_b64_tr_b16 v[196:197], v176 offset:38912
	s_waitcnt lgkmcnt(6)
	v_mfma_f32_32x32x16_bf16 v[80:95], v[226:229], v[116:119], v[80:95]
	ds_read_b64_tr_b16 v[200:201], v176 offset:40960
	ds_read_b64_tr_b16 v[202:203], v176 offset:43008
	ds_read_b64_tr_b16 v[204:205], v176 offset:45056
	ds_read_b64_tr_b16 v[206:207], v176 offset:47104
	s_add_i32 s74, s40, 0x4000
	s_and_b32 s74, s74, 0xc000
	s_add_u32 s98, s38, s22
	s_addc_u32 s99, s39, s23
	s_add_i32 s41, s67, s74
	s_add_u32 s100, s38, s24
	s_addc_u32 s101, s39, s25
	s_mov_b32 m0, s41
	s_add_i32 s74, s72, s74
	global_load_lds_dwordx4 v156, s[98:99]
	s_waitcnt lgkmcnt(9)
; #define SBAR() __builtin_amdgcn_sched_barrier(0)
; #define PUBLISH(n) do { asm volatile("s_waitcnt vmcnt(" #n ")" ::: "memory"); asm volatile("s_waitcnt lgkmcnt(0)" ::: "memory"); __builtin_amdgcn_s_barrier(); SBAR(); } while (0)
; template <int D0> __device__ __forceinline__ void pv_one(f32x16& od, int vb, bf16x8 pa0, bf16x8 pa1, bf16x8 pa2, bf16x8 pa3) {
;   const s16x4 l0 = tr_read<v_rd_off(D0, 0, 0)>(vb), h0 = tr_read<v_rd_off(D0, 0, 1)>(vb), l1 = tr_read<v_rd_off(D0, 1, 0)>(vb), h1 = tr_read<v_rd_off(D0, 1, 1)>(vb);
;   const s16x4 l2 = tr_read<v_rd_off(D0, 2, 0)>(vb), h2 = tr_read<v_rd_off(D0, 2, 1)>(vb), l3 = tr_read<v_rd_off(D0, 3, 0)>(vb), h3 = tr_read<v_rd_off(D0, 3, 1)>(vb);
;   asm volatile("s_waitcnt lgkmcnt(0)" ::: "memory"); SBAR();
;     ...
;   od = __builtin_amdgcn_mfma_f32_32x32x16_bf16(pa0, PK(l0, h0), od, 0, 0, 0);
;   od = __builtin_amdgcn_mfma_f32_32x32x16_bf16(pa1, PK(l1, h1), od, 0, 0, 0);
;   od = __builtin_amdgcn_mfma_f32_32x32x16_bf16(pa2, PK(l2, h2), od, 0, 0, 0);
;   od = __builtin_amdgcn_mfma_f32_32x32x16_bf16(pa3, PK(l3, h3), od, 0, 0, 0);
;     ...
; }
; __device__ __forceinline__ void pv_d0(f32x16* o, int vb, bf16x8 pa0, bf16x8 pa1, bf16x8 pa2, bf16x8 pa3) {
;   pv_one<0>(o[0], vb, pa0, pa1, pa2, pa3); pv_one<1>(o[1], vb, pa0, pa1, pa2, pa3); pv_one<2>(o[2], vb, pa0, pa1, pa2, pa3); pv_one<3>(o[3], vb, pa0, pa1, pa2, pa3);
; }
; template <typename TQ> ...
;     ...
;   for (int j = 1; j + 1 < NT; j += 2) {
;     SBAR(); qkt(pB0, pB1, (const bf16*)(K_lds + (j & 3) * (int)SHM_K), qr, r32, hi);
;     finishSM(pA0, pA1, alA, l_reg, pa0, pa1, pa2, pa3); SBAR();
;     DMA_TILE(j + 2, (j + 2) & 3); SBAR();
;     pv_d0(o, vb0 + ((j - 1) & 3) * (int)SHM_V, pa0, pa1, pa2, pa3); partialSM<true>(pB0, pB1, m_reg, mnB, alB);
;     PUBLISH(4);
;     SBAR(); qkt(pA0, pA1, (const bf16*)(K_lds + ((j + 1) & 3) * (int)SHM_K), qr, r32, hi);
;     finishSM(pB0, pB1, alB, l_reg, pa0, pa1, pa2, pa3); SBAR();
;     if (j + 3 < NT) { DMA_TILE(j + 3, (j + 3) & 3); } SBAR();
;     pv_d0(o, vb0 + (j & 3) * (int)SHM_V, pa0, pa1, pa2, pa3); partialSM<true>(pA0, pA1, m_reg, mnA, alA);
;     if (j + 3 < NT) { PUBLISH(4); } else { PUBLISH(0); }
;   }
	v_mfma_f32_32x32x16_bf16 v[96:111], v[230:233], v[112:115], v[96:111]
	s_add_i32 m0, s41, 0x2000
	s_nop 0
	global_load_lds_dwordx4 v158, s[98:99]
	s_mov_b32 m0, s74
	s_nop 0
	global_load_lds_dwordx4 v162, s[100:101]
	s_waitcnt lgkmcnt(8)
	v_mfma_f32_32x32x16_bf16 v[80:95], v[234:237], v[112:115], v[80:95]
	s_add_i32 m0, s74, 0x2000
	s_nop 0
	global_load_lds_dwordx4 v160, s[100:101]
	s_nop 0
	s_waitcnt lgkmcnt(6)
	v_mfma_f32_32x32x16_bf16 v[48:63], v[64:67], v[190:193], v[48:63]
	v_exp_f32_e32 v232, v96
	ds_read_b64_tr_b16 v[190:191], v176 offset:33280
	ds_read_b64_tr_b16 v[192:193], v176 offset:35328
	s_waitcnt lgkmcnt(6)
	v_mfma_f32_32x32x16_bf16 v[48:63], v[68:71], v[194:197], v[48:63]
	v_exp_f32_e32 v233, v97
	ds_read_b64_tr_b16 v[194:195], v176 offset:37376
	ds_read_b64_tr_b16 v[196:197], v176 offset:39424
	s_waitcnt lgkmcnt(6)
	v_mfma_f32_32x32x16_bf16 v[48:63], v[72:75], v[200:203], v[48:63]
	v_exp_f32_e32 v234, v98
	ds_read_b64_tr_b16 v[200:201], v176 offset:41472
	ds_read_b64_tr_b16 v[202:203], v176 offset:43520
	ds_read_b64_tr_b16 v[208:209], v176 offset:45568
	ds_read_b64_tr_b16 v[210:211], v176 offset:47616
	s_waitcnt lgkmcnt(8)
	v_mfma_f32_32x32x16_bf16 v[48:63], v[76:79], v[204:207], v[48:63]
	v_exp_f32_e32 v235, v99
	s_waitcnt lgkmcnt(6)
	v_mfma_f32_32x32x16_bf16 v[32:47], v[64:67], v[190:193], v[32:47]
	v_exp_f32_e32 v236, v100
	ds_read_b64_tr_b16 v[190:191], v176 offset:33792
	ds_read_b64_tr_b16 v[192:193], v176 offset:35840
	s_waitcnt lgkmcnt(6)
	v_mfma_f32_32x32x16_bf16 v[32:47], v[68:71], v[194:197], v[32:47]
	v_exp_f32_e32 v237, v101
	ds_read_b64_tr_b16 v[194:195], v176 offset:37888
	ds_read_b64_tr_b16 v[196:197], v176 offset:39936
	s_waitcnt lgkmcnt(6)
	v_mfma_f32_32x32x16_bf16 v[32:47], v[72:75], v[200:203], v[32:47]
	v_exp_f32_e32 v238, v102
	ds_read_b64_tr_b16 v[200:201], v176 offset:41984
	ds_read_b64_tr_b16 v[202:203], v176 offset:44032
	ds_read_b64_tr_b16 v[204:205], v176 offset:46080
	ds_read_b64_tr_b16 v[206:207], v176 offset:48128
	s_waitcnt lgkmcnt(8)
	v_mfma_f32_32x32x16_bf16 v[32:47], v[76:79], v[208:211], v[32:47]
	v_exp_f32_e32 v239, v103
	v_exp_f32_e32 v240, v104
	s_waitcnt lgkmcnt(6)
	v_mfma_f32_32x32x16_bf16 v[16:31], v[64:67], v[190:193], v[16:31]
	v_exp_f32_e32 v241, v105
	ds_read_b64_tr_b16 v[190:191], v176 offset:34304
	ds_read_b64_tr_b16 v[192:193], v176 offset:36352
	s_waitcnt lgkmcnt(6)
	v_mfma_f32_32x32x16_bf16 v[16:31], v[68:71], v[194:197], v[16:31]
	v_exp_f32_e32 v242, v106
	ds_read_b64_tr_b16 v[194:195], v176 offset:38400
	ds_read_b64_tr_b16 v[196:197], v176 offset:40448
	s_waitcnt lgkmcnt(6)
	v_mfma_f32_32x32x16_bf16 v[16:31], v[72:75], v[200:203], v[16:31]
	v_exp_f32_e32 v243, v107
	ds_read_b64_tr_b16 v[200:201], v176 offset:42496
	ds_read_b64_tr_b16 v[202:203], v176 offset:44544
	ds_read_b64_tr_b16 v[208:209], v176 offset:46592
	ds_read_b64_tr_b16 v[210:211], v176 offset:48640
	s_waitcnt lgkmcnt(8)
	v_mfma_f32_32x32x16_bf16 v[16:31], v[76:79], v[204:207], v[16:31]
	v_exp_f32_e32 v244, v108
	s_waitcnt lgkmcnt(6)
	v_mfma_f32_32x32x16_bf16 v[0:15], v[64:67], v[190:193], v[0:15]
	v_exp_f32_e32 v245, v109
	s_waitcnt lgkmcnt(4)
	v_mfma_f32_32x32x16_bf16 v[0:15], v[68:71], v[194:197], v[0:15]
	v_exp_f32_e32 v246, v110
	s_waitcnt lgkmcnt(2)
	v_mfma_f32_32x32x16_bf16 v[0:15], v[72:75], v[200:203], v[0:15]
	v_exp_f32_e32 v247, v111
	s_waitcnt vmcnt(4)
	s_waitcnt lgkmcnt(0)
	s_barrier
	v_mfma_f32_32x32x16_bf16 v[0:15], v[76:79], v[208:211], v[0:15]
	s_and_b32 s40, s40, 0xc000
	s_add_i32 s40, s57, s40
	ds_read_b128 v[64:67], v178
	ds_read_b128 v[68:71], v178 offset:8192
	ds_read_b128 v[190:193], v179
	ds_read_b128 v[194:197], v179 offset:8192
	v_exp_f32_e32 v80, v80
	v_exp_f32_e32 v81, v81
	v_exp_f32_e32 v82, v82
	v_exp_f32_e32 v83, v83
	v_exp_f32_e32 v87, v87
	v_exp_f32_e32 v248, v93
	v_exp_f32_e32 v249, v94
	s_waitcnt lgkmcnt(3)
	v_mfma_f32_32x32x16_bf16 v[96:111], v[64:67], v[136:139], 0
	s_waitcnt lgkmcnt(2)
	v_mfma_f32_32x32x16_bf16 v[64:79], v[68:71], v[136:139], 0
	s_waitcnt lgkmcnt(1)
	v_mfma_f32_32x32x16_bf16 v[96:111], v[190:193], v[140:143], v[96:111]
	s_waitcnt lgkmcnt(0)
	v_mfma_f32_32x32x16_bf16 v[64:79], v[194:197], v[140:143], v[64:79]
	ds_read_b128 v[190:193], v180
	ds_read_b128 v[194:197], v180 offset:8192
	s_waitcnt lgkmcnt(1)
	v_mfma_f32_32x32x16_bf16 v[96:111], v[190:193], v[132:135], v[96:111]
	ds_read_b128 v[190:193], v181
	ds_read_b128 v[200:203], v181 offset:8192
	ds_read_b128 v[204:207], v182
	ds_read_b128 v[208:211], v182 offset:8192
	ds_read_b128 v[212:215], v183
	ds_read_b128 v[216:219], v183 offset:8192
	s_waitcnt lgkmcnt(6)
	v_mfma_f32_32x32x16_bf16 v[64:79], v[194:197], v[132:135], v[64:79]
	ds_read_b128 v[194:197], v184
	ds_read_b128 v[220:223], v184 offset:8192
	ds_read_b128 v[224:227], v185
	ds_read_b128 v[228:231], v185 offset:8192
	s_waitcnt lgkmcnt(9)
	v_mfma_f32_32x32x16_bf16 v[96:111], v[190:193], v[128:131], v[96:111]
	s_cmp_ge_u32 s73, s37
	s_cselect_b64 s[40:41], -1, 0
	s_and_b64 vcc, exec, s[40:41]
	s_cbranch_vccnz .Lat463_b

; #define SBAR() __builtin_amdgcn_sched_barrier(0)
; template <typename TQ> ...
;     ...
;     if (j + 3 < NT) { DMA_TILE(j + 3, (j + 3) & 3); } SBAR();
	s_add_i32 s74, s67, s43
	s_add_u32 s98, s38, s26
	s_addc_u32 s99, s39, s27
	s_mov_b32 m0, s74
	s_add_i32 s43, s72, s43
	global_load_lds_dwordx4 v156, s[98:99]
	s_add_u32 s100, s38, s28
	s_addc_u32 s101, s39, s29
	s_add_i32 m0, s74, 0x2000
	s_nop 0
	global_load_lds_dwordx4 v158, s[98:99]
	s_mov_b32 m0, s43
	s_nop 0
	global_load_lds_dwordx4 v162, s[100:101]
	s_add_i32 m0, s43, 0x2000
	s_nop 0
	global_load_lds_dwordx4 v160, s[100:101]

; #define SBAR() __builtin_amdgcn_sched_barrier(0)
; #define PK4(P, BASE, OUT) do { u32x4 w = {cvtpk(P[BASE + 0], P[BASE + 1]), cvtpk(P[BASE + 2], P[BASE + 3]), cvtpk(P[BASE + 4], P[BASE + 5]), cvtpk(P[BASE + 6], P[BASE + 7])}; \
;     OUT = *reinterpret_cast<bf16x8*>(&w); } while (0)
; #define PUBLISH(n) do { asm volatile("s_waitcnt vmcnt(" #n ")" ::: "memory"); asm volatile("s_waitcnt lgkmcnt(0)" ::: "memory"); __builtin_amdgcn_s_barrier(); SBAR(); } while (0)
; __device__ __forceinline__ void finishSM(f32x16& p0, f32x16& p1, float alpha, float& l_reg, bf16x8& pa0, bf16x8& pa1, bf16x8& pa2, bf16x8& pa3) {
;   for (int r = 0; r < 16; ++r) p1[r] = __builtin_amdgcn_exp2f(p1[r]);
;   float ps = 0; for (int r = 0; r < 16; ++r) ps += p0[r]; for (int r = 0; r < 16; ++r) ps += p1[r];
;   asm volatile("" : "+v"(ps));
;   l_reg = l_reg * alpha + ps;
;     ...
;   PK4(p0, 0, pa0); PK4(p0, 8, pa1); PK4(p1, 0, pa2); PK4(p1, 8, pa3);
;     ...
; }
; __device__ __forceinline__ void qkt(f32x16& p0, f32x16& p1, const bf16* Ks, const bf16x8* qr, int r32, int hi) {
;   p0 = f32x16{}; p1 = f32x16{};
;   for (int d0 = 0; d0 < 8; ++d0) { int cb = (d0 * 16 + hi * 8) * 2;
;     bf16x8 b0 = *reinterpret_cast<const bf16x8*>((const char*)Ks + KSWZ(r32, cb));
;     bf16x8 b1 = *reinterpret_cast<const bf16x8*>((const char*)Ks + KSWZ(32 + r32, cb));
;     p0 = __builtin_amdgcn_mfma_f32_32x32x16_bf16(b0, qr[d0], p0, 0, 0, 0);
;     p1 = __builtin_amdgcn_mfma_f32_32x32x16_bf16(b1, qr[d0], p1, 0, 0, 0); }
; }
; template <typename TQ> ...
;     ...
;   for (int j = 1; j + 1 < NT; j += 2) {
;     SBAR(); qkt(pB0, pB1, (const bf16*)(K_lds + (j & 3) * (int)SHM_K), qr, r32, hi);
;     finishSM(pA0, pA1, alA, l_reg, pa0, pa1, pa2, pa3); SBAR();
;     DMA_TILE(j + 2, (j + 2) & 3); SBAR();
;     pv_d0(o, vb0 + ((j - 1) & 3) * (int)SHM_V, pa0, pa1, pa2, pa3); partialSM<true>(pB0, pB1, m_reg, mnB, alB);
;     PUBLISH(4);
;     SBAR(); qkt(pA0, pA1, (const bf16*)(K_lds + ((j + 1) & 3) * (int)SHM_K), qr, r32, hi);
;     finishSM(pB0, pB1, alB, l_reg, pa0, pa1, pa2, pa3); SBAR();
;     if (j + 3 < NT) { DMA_TILE(j + 3, (j + 3) & 3); } SBAR();
;     pv_d0(o, vb0 + (j & 3) * (int)SHM_V, pa0, pa1, pa2, pa3); partialSM<true>(pA0, pA1, m_reg, mnA, alA);
.Lat1365_a_go:
	s_waitcnt lgkmcnt(3)
	v_mfma_f32_32x32x16_bf16 v[96:111], v[80:83], v[136:139], 0
	v_exp_f32_e32 v238, v64
	v_add_f32_e32 v64, v197, v196
	v_add_f32_e32 v64, v193, v64
	v_add_f32_e32 v64, v195, v64
	s_waitcnt lgkmcnt(2)
	v_mfma_f32_32x32x16_bf16 v[80:95], v[84:87], v[136:139], 0
	v_add_f32_e32 v64, v191, v64
	v_add_f32_e32 v64, v194, v64
	v_add_f32_e32 v64, v190, v64
	v_add_f32_e32 v64, v192, v64
	v_add_f32_e32 v64, v169, v64
	v_add_f32_e32 v64, v171, v64
	s_waitcnt lgkmcnt(1)
	v_mfma_f32_32x32x16_bf16 v[96:111], v[198:201], v[140:143], v[96:111]
	v_add_f32_e32 v64, v167, v64
	v_add_f32_e32 v64, v170, v64
	v_add_f32_e32 v64, v165, v64
	v_add_f32_e32 v64, v168, v64
	v_add_f32_e32 v64, v164, v64
	v_add_f32_e32 v64, v166, v64
	v_exp_f32_e32 v239, v68
	s_waitcnt lgkmcnt(0)
	v_mfma_f32_32x32x16_bf16 v[80:95], v[202:205], v[140:143], v[80:95]
	ds_read_b128 v[198:201], v180 offset:16384
	ds_read_b128 v[202:205], v180 offset:24576
	v_add_f32_e32 v64, v238, v64
	v_exp_f32_e32 v240, v69
	v_exp_f32_e32 v241, v70
	v_exp_f32_e32 v242, v71
	s_waitcnt lgkmcnt(1)
	v_mfma_f32_32x32x16_bf16 v[96:111], v[198:201], v[132:135], v[96:111]
	ds_read_b128 v[198:201], v181 offset:16384
	ds_read_b128 v[206:209], v181 offset:24576
	ds_read_b128 v[210:213], v182 offset:16384
	ds_read_b128 v[214:217], v182 offset:24576
	ds_read_b128 v[218:221], v183 offset:16384
	ds_read_b128 v[222:225], v183 offset:24576
	v_exp_f32_e32 v243, v76
	v_exp_f32_e32 v244, v77
	v_exp_f32_e32 v245, v78
	v_exp_f32_e32 v79, v79
	s_waitcnt lgkmcnt(6)
	v_mfma_f32_32x32x16_bf16 v[80:95], v[202:205], v[132:135], v[80:95]
	ds_read_b128 v[202:205], v184 offset:16384
	ds_read_b128 v[226:229], v184 offset:24576
	ds_read_b128 v[230:233], v185 offset:16384
	ds_read_b128 v[234:237], v185 offset:24576
	s_waitcnt lgkmcnt(9)
	v_mfma_f32_32x32x16_bf16 v[96:111], v[198:201], v[128:131], v[96:111]
	v_exp_f32_e32 v199, v65
	v_exp_f32_e32 v200, v66
	v_exp_f32_e32 v201, v67
	v_add_f32_e32 v64, v199, v64
	v_add_f32_e32 v64, v200, v64
	v_add_f32_e32 v64, v201, v64
	s_waitcnt lgkmcnt(8)
	v_mfma_f32_32x32x16_bf16 v[80:95], v[206:209], v[128:131], v[80:95]
	v_exp_f32_e32 v206, v72
	v_add_f32_e32 v64, v239, v64
	v_exp_f32_e32 v207, v73
	v_add_f32_e32 v64, v240, v64
	v_exp_f32_e32 v208, v74
	v_add_f32_e32 v64, v241, v64
	v_exp_f32_e32 v209, v75
	s_waitcnt lgkmcnt(7)
	v_mfma_f32_32x32x16_bf16 v[96:111], v[210:213], v[124:127], v[96:111]
	v_add_f32_e32 v64, v242, v64
	v_add_f32_e32 v64, v206, v64
	v_add_f32_e32 v64, v207, v64
	v_add_f32_e32 v64, v208, v64
	v_add_f32_e32 v64, v209, v64
	v_add_f32_e32 v64, v243, v64
	v_add_f32_e32 v64, v244, v64
	s_waitcnt lgkmcnt(6)
	v_mfma_f32_32x32x16_bf16 v[80:95], v[214:217], v[124:127], v[80:95]
	v_add_f32_e32 v64, v245, v64
	v_add_f32_e32 v198, v79, v64
	v_cvt_pk_bf16_f32 v64, v196, v197
	v_cvt_pk_bf16_f32 v65, v193, v195
	v_cvt_pk_bf16_f32 v66, v191, v194
	v_cvt_pk_bf16_f32 v67, v190, v192
	s_waitcnt lgkmcnt(5)
	v_mfma_f32_32x32x16_bf16 v[96:111], v[218:221], v[120:123], v[96:111]
	v_cvt_pk_bf16_f32 v68, v169, v171
	v_cvt_pk_bf16_f32 v69, v167, v170
	v_cvt_pk_bf16_f32 v70, v165, v168
	v_cvt_pk_bf16_f32 v71, v164, v166
	v_cvt_pk_bf16_f32 v72, v238, v199
	v_cvt_pk_bf16_f32 v73, v200, v201
	v_cvt_pk_bf16_f32 v74, v239, v240
	s_waitcnt lgkmcnt(4)
	v_mfma_f32_32x32x16_bf16 v[80:95], v[222:225], v[120:123], v[80:95]
	v_cvt_pk_bf16_f32 v75, v241, v242
	v_cvt_pk_bf16_f32 v76, v206, v207
	v_cvt_pk_bf16_f32 v77, v208, v209
	v_cvt_pk_bf16_f32 v78, v243, v244
	v_cvt_pk_bf16_f32 v79, v245, v79
	s_waitcnt lgkmcnt(3)
	v_mfma_f32_32x32x16_bf16 v[96:111], v[202:205], v[116:119], v[96:111]
	s_add_i32 s33, s40, 0x8000
	s_and_b32 s43, s33, 0xc000
	ds_read_b64_tr_b16 v[190:191], v176
	ds_read_b64_tr_b16 v[192:193], v176 offset:2048
	ds_read_b64_tr_b16 v[194:195], v176 offset:4096
	ds_read_b64_tr_b16 v[196:197], v176 offset:6144
	s_waitcnt lgkmcnt(6)
	v_mfma_f32_32x32x16_bf16 v[80:95], v[226:229], v[116:119], v[80:95]
	ds_read_b64_tr_b16 v[200:201], v176 offset:8192
	ds_read_b64_tr_b16 v[202:203], v176 offset:10240
	ds_read_b64_tr_b16 v[204:205], v176 offset:12288
	ds_read_b64_tr_b16 v[206:207], v176 offset:14336
	s_add_i32 s73, s40, 0x4000
	s_and_b32 s73, s73, 0xc000
	s_add_u32 s98, s38, s22
	s_addc_u32 s99, s39, s23
	s_add_i32 s41, s66, s73
	s_add_u32 s100, s38, s24
	s_addc_u32 s101, s39, s25
	s_mov_b32 m0, s41
	s_add_i32 s73, s67, s73
	global_load_lds_dwordx4 v156, s[98:99]
	s_waitcnt lgkmcnt(9)
	v_mfma_f32_32x32x16_bf16 v[96:111], v[230:233], v[112:115], v[96:111]
	s_add_i32 m0, s41, 0x2000
	s_nop 0
	global_load_lds_dwordx4 v158, s[98:99]
	s_mov_b32 m0, s73
	s_nop 0
	global_load_lds_dwordx4 v162, s[100:101]
	s_waitcnt lgkmcnt(8)
	v_mfma_f32_32x32x16_bf16 v[80:95], v[234:237], v[112:115], v[80:95]
	s_add_i32 m0, s73, 0x2000
	s_nop 0
	global_load_lds_dwordx4 v160, s[100:101]
	s_nop 0
	s_waitcnt lgkmcnt(6)
	v_mfma_f32_32x32x16_bf16 v[48:63], v[64:67], v[190:193], v[48:63]
	v_exp_f32_e32 v232, v96
	ds_read_b64_tr_b16 v[190:191], v176 offset:512
	ds_read_b64_tr_b16 v[192:193], v176 offset:2560
	s_waitcnt lgkmcnt(6)
; #define SBAR() __builtin_amdgcn_sched_barrier(0)
; #define PUBLISH(n) do { asm volatile("s_waitcnt vmcnt(" #n ")" ::: "memory"); asm volatile("s_waitcnt lgkmcnt(0)" ::: "memory"); __builtin_amdgcn_s_barrier(); SBAR(); } while (0)
; template <int D0> __device__ __forceinline__ void pv_one(f32x16& od, int vb, bf16x8 pa0, bf16x8 pa1, bf16x8 pa2, bf16x8 pa3) {
;   const s16x4 l0 = tr_read<v_rd_off(D0, 0, 0)>(vb), h0 = tr_read<v_rd_off(D0, 0, 1)>(vb), l1 = tr_read<v_rd_off(D0, 1, 0)>(vb), h1 = tr_read<v_rd_off(D0, 1, 1)>(vb);
;   const s16x4 l2 = tr_read<v_rd_off(D0, 2, 0)>(vb), h2 = tr_read<v_rd_off(D0, 2, 1)>(vb), l3 = tr_read<v_rd_off(D0, 3, 0)>(vb), h3 = tr_read<v_rd_off(D0, 3, 1)>(vb);
;   asm volatile("s_waitcnt lgkmcnt(0)" ::: "memory"); SBAR();
;     ...
;   od = __builtin_amdgcn_mfma_f32_32x32x16_bf16(pa0, PK(l0, h0), od, 0, 0, 0);
;   od = __builtin_amdgcn_mfma_f32_32x32x16_bf16(pa1, PK(l1, h1), od, 0, 0, 0);
;   od = __builtin_amdgcn_mfma_f32_32x32x16_bf16(pa2, PK(l2, h2), od, 0, 0, 0);
;   od = __builtin_amdgcn_mfma_f32_32x32x16_bf16(pa3, PK(l3, h3), od, 0, 0, 0);
;     ...
; }
; __device__ __forceinline__ void pv_d0(f32x16* o, int vb, bf16x8 pa0, bf16x8 pa1, bf16x8 pa2, bf16x8 pa3) {
;   pv_one<0>(o[0], vb, pa0, pa1, pa2, pa3); pv_one<1>(o[1], vb, pa0, pa1, pa2, pa3); pv_one<2>(o[2], vb, pa0, pa1, pa2, pa3); pv_one<3>(o[3], vb, pa0, pa1, pa2, pa3);
; }
; template <typename TQ> ...
;     ...
;   for (int j = 1; j + 1 < NT; j += 2) {
;     SBAR(); qkt(pB0, pB1, (const bf16*)(K_lds + (j & 3) * (int)SHM_K), qr, r32, hi);
;     finishSM(pA0, pA1, alA, l_reg, pa0, pa1, pa2, pa3); SBAR();
;     DMA_TILE(j + 2, (j + 2) & 3); SBAR();
;     pv_d0(o, vb0 + ((j - 1) & 3) * (int)SHM_V, pa0, pa1, pa2, pa3); partialSM<true>(pB0, pB1, m_reg, mnB, alB);
;     PUBLISH(4);
;     SBAR(); qkt(pA0, pA1, (const bf16*)(K_lds + ((j + 1) & 3) * (int)SHM_K), qr, r32, hi);
	v_mfma_f32_32x32x16_bf16 v[48:63], v[68:71], v[194:197], v[48:63]
	v_exp_f32_e32 v233, v97
	ds_read_b64_tr_b16 v[194:195], v176 offset:4608
	ds_read_b64_tr_b16 v[196:197], v176 offset:6656
	s_waitcnt lgkmcnt(6)
	v_mfma_f32_32x32x16_bf16 v[48:63], v[72:75], v[200:203], v[48:63]
	v_exp_f32_e32 v234, v98
	ds_read_b64_tr_b16 v[200:201], v176 offset:8704
	ds_read_b64_tr_b16 v[202:203], v176 offset:10752
	ds_read_b64_tr_b16 v[208:209], v176 offset:12800
	ds_read_b64_tr_b16 v[210:211], v176 offset:14848
	s_waitcnt lgkmcnt(8)
	v_mfma_f32_32x32x16_bf16 v[48:63], v[76:79], v[204:207], v[48:63]
	v_exp_f32_e32 v235, v99
	s_waitcnt lgkmcnt(6)
	v_mfma_f32_32x32x16_bf16 v[32:47], v[64:67], v[190:193], v[32:47]
	v_exp_f32_e32 v236, v100
	ds_read_b64_tr_b16 v[190:191], v176 offset:1024
	ds_read_b64_tr_b16 v[192:193], v176 offset:3072
	s_waitcnt lgkmcnt(6)
	v_mfma_f32_32x32x16_bf16 v[32:47], v[68:71], v[194:197], v[32:47]
	v_exp_f32_e32 v237, v101
	ds_read_b64_tr_b16 v[194:195], v176 offset:5120
	ds_read_b64_tr_b16 v[196:197], v176 offset:7168
	s_waitcnt lgkmcnt(6)
	v_mfma_f32_32x32x16_bf16 v[32:47], v[72:75], v[200:203], v[32:47]
	v_exp_f32_e32 v238, v102
	ds_read_b64_tr_b16 v[200:201], v176 offset:9216
	ds_read_b64_tr_b16 v[202:203], v176 offset:11264
	ds_read_b64_tr_b16 v[204:205], v176 offset:13312
	ds_read_b64_tr_b16 v[206:207], v176 offset:15360
	s_waitcnt lgkmcnt(8)
	v_mfma_f32_32x32x16_bf16 v[32:47], v[76:79], v[208:211], v[32:47]
	v_exp_f32_e32 v239, v103
	v_exp_f32_e32 v240, v104
	s_waitcnt lgkmcnt(6)
	v_mfma_f32_32x32x16_bf16 v[16:31], v[64:67], v[190:193], v[16:31]
	v_exp_f32_e32 v241, v105
	ds_read_b64_tr_b16 v[190:191], v176 offset:1536
	ds_read_b64_tr_b16 v[192:193], v176 offset:3584
	s_waitcnt lgkmcnt(6)
	v_mfma_f32_32x32x16_bf16 v[16:31], v[68:71], v[194:197], v[16:31]
	v_exp_f32_e32 v242, v106
	ds_read_b64_tr_b16 v[194:195], v176 offset:5632
	ds_read_b64_tr_b16 v[196:197], v176 offset:7680
	s_waitcnt lgkmcnt(6)
	v_mfma_f32_32x32x16_bf16 v[16:31], v[72:75], v[200:203], v[16:31]
	v_exp_f32_e32 v243, v107
	ds_read_b64_tr_b16 v[200:201], v176 offset:9728
	ds_read_b64_tr_b16 v[202:203], v176 offset:11776
	ds_read_b64_tr_b16 v[208:209], v176 offset:13824
	ds_read_b64_tr_b16 v[210:211], v176 offset:15872
	s_waitcnt lgkmcnt(8)
	v_mfma_f32_32x32x16_bf16 v[16:31], v[76:79], v[204:207], v[16:31]
	v_exp_f32_e32 v244, v108
	s_waitcnt lgkmcnt(6)
	v_mfma_f32_32x32x16_bf16 v[0:15], v[64:67], v[190:193], v[0:15]
	v_exp_f32_e32 v245, v109
	s_waitcnt lgkmcnt(4)
	v_mfma_f32_32x32x16_bf16 v[0:15], v[68:71], v[194:197], v[0:15]
	v_exp_f32_e32 v246, v110
	s_waitcnt lgkmcnt(2)
	v_mfma_f32_32x32x16_bf16 v[0:15], v[72:75], v[200:203], v[0:15]
	v_exp_f32_e32 v247, v111
	s_waitcnt vmcnt(4)
	s_waitcnt lgkmcnt(0)
	s_barrier
	v_mfma_f32_32x32x16_bf16 v[0:15], v[76:79], v[208:211], v[0:15]
	s_and_b32 s40, s40, 0xc000
	s_add_i32 s40, s56, s40
	ds_read_b128 v[64:67], v178 offset:32768
	ds_read_b128 v[68:71], v178 offset:40960
	ds_read_b128 v[190:193], v179 offset:32768
	ds_read_b128 v[194:197], v179 offset:40960
	v_exp_f32_e32 v80, v80
	v_exp_f32_e32 v81, v81
	v_exp_f32_e32 v82, v82
	v_exp_f32_e32 v83, v83
	v_exp_f32_e32 v87, v87
	v_exp_f32_e32 v248, v93
	v_exp_f32_e32 v249, v94
	s_waitcnt lgkmcnt(3)
	v_mfma_f32_32x32x16_bf16 v[96:111], v[64:67], v[136:139], 0
	s_waitcnt lgkmcnt(2)
	v_mfma_f32_32x32x16_bf16 v[64:79], v[68:71], v[136:139], 0
	s_waitcnt lgkmcnt(1)
	v_mfma_f32_32x32x16_bf16 v[96:111], v[190:193], v[140:143], v[96:111]
	s_waitcnt lgkmcnt(0)
	v_mfma_f32_32x32x16_bf16 v[64:79], v[194:197], v[140:143], v[64:79]
	ds_read_b128 v[190:193], v180 offset:32768
	ds_read_b128 v[194:197], v180 offset:40960
	s_waitcnt lgkmcnt(1)
	v_mfma_f32_32x32x16_bf16 v[96:111], v[190:193], v[132:135], v[96:111]
	ds_read_b128 v[190:193], v181 offset:32768
	ds_read_b128 v[200:203], v181 offset:40960
	ds_read_b128 v[204:207], v182 offset:32768
	ds_read_b128 v[208:211], v182 offset:40960
	ds_read_b128 v[212:215], v183 offset:32768
	ds_read_b128 v[216:219], v183 offset:40960
	s_waitcnt lgkmcnt(6)
	v_mfma_f32_32x32x16_bf16 v[64:79], v[194:197], v[132:135], v[64:79]
	ds_read_b128 v[194:197], v184 offset:32768
	ds_read_b128 v[220:223], v184 offset:40960
	ds_read_b128 v[224:227], v185 offset:32768
	ds_read_b128 v[228:231], v185 offset:40960
	s_waitcnt lgkmcnt(9)
	v_mfma_f32_32x32x16_bf16 v[96:111], v[190:193], v[128:131], v[96:111]
	s_cmp_ge_u32 s72, s37
	s_cselect_b64 s[40:41], -1, 0
	s_and_b64 vcc, exec, s[40:41]
	s_cbranch_vccnz .LBB0_1367
	s_add_i32 s73, s66, s43
	s_add_u32 s98, s38, s26
	s_addc_u32 s99, s39, s27
	s_mov_b32 m0, s73
	s_add_i32 s43, s67, s43
	global_load_lds_dwordx4 v156, s[98:99]
	s_add_u32 s100, s38, s28
	s_addc_u32 s101, s39, s29
	s_add_i32 m0, s73, 0x2000
	s_nop 0
	global_load_lds_dwordx4 v158, s[98:99]
	s_mov_b32 m0, s43
	s_nop 0
	global_load_lds_dwordx4 v162, s[100:101]
	s_add_i32 m0, s43, 0x2000
	s_nop 0
	global_load_lds_dwordx4 v160, s[100:101]

; #define SBAR() __builtin_amdgcn_sched_barrier(0)
; #define PK4(P, BASE, OUT) do { u32x4 w = {cvtpk(P[BASE + 0], P[BASE + 1]), cvtpk(P[BASE + 2], P[BASE + 3]), cvtpk(P[BASE + 4], P[BASE + 5]), cvtpk(P[BASE + 6], P[BASE + 7])}; \
;     OUT = *reinterpret_cast<bf16x8*>(&w); } while (0)
; __device__ __forceinline__ void finishSM(f32x16& p0, f32x16& p1, float alpha, float& l_reg, bf16x8& pa0, bf16x8& pa1, bf16x8& pa2, bf16x8& pa3) {
;   for (int r = 0; r < 16; ++r) p1[r] = __builtin_amdgcn_exp2f(p1[r]);
;   float ps = 0; for (int r = 0; r < 16; ++r) ps += p0[r]; for (int r = 0; r < 16; ++r) ps += p1[r];
;   asm volatile("" : "+v"(ps));
;   l_reg = l_reg * alpha + ps;
;     ...
;   PK4(p0, 0, pa0); PK4(p0, 8, pa1); PK4(p1, 0, pa2); PK4(p1, 8, pa3);
;     ...
; }
; __device__ __forceinline__ void qkt(f32x16& p0, f32x16& p1, const bf16* Ks, const bf16x8* qr, int r32, int hi) {
;   p0 = f32x16{}; p1 = f32x16{};
;   for (int d0 = 0; d0 < 8; ++d0) { int cb = (d0 * 16 + hi * 8) * 2;
;     bf16x8 b0 = *reinterpret_cast<const bf16x8*>((const char*)Ks + KSWZ(r32, cb));
;     bf16x8 b1 = *reinterpret_cast<const bf16x8*>((const char*)Ks + KSWZ(32 + r32, cb));
;     p0 = __builtin_amdgcn_mfma_f32_32x32x16_bf16(b0, qr[d0], p0, 0, 0, 0);
;     p1 = __builtin_amdgcn_mfma_f32_32x32x16_bf16(b1, qr[d0], p1, 0, 0, 0); }
; }
; template <typename TQ> ...
;     ...
;     SBAR(); qkt(pA0, pA1, (const bf16*)(K_lds + ((j + 1) & 3) * (int)SHM_K), qr, r32, hi);
;     finishSM(pB0, pB1, alB, l_reg, pa0, pa1, pa2, pa3); SBAR();
;     if (j + 3 < NT) { DMA_TILE(j + 3, (j + 3) & 3); } SBAR();
;     pv_d0(o, vb0 + (j & 3) * (int)SHM_V, pa0, pa1, pa2, pa3); partialSM<true>(pA0, pA1, m_reg, mnA, alA);
.Lat1365_b:
.Lat1365_b_in:
	s_mov_b32 s40, s33
	s_addk_i32 s33, 0xc000
	s_and_b32 s42, s33, 0xc000
	s_add_i32 s33, s56, s42
	ds_read_b128 v[80:83], v178 offset:49152
	ds_read_b128 v[84:87], v178 offset:57344
	ds_read_b128 v[198:201], v179 offset:49152
	ds_read_b128 v[202:205], v179 offset:57344
	v_exp_f32_e32 v196, v96
	v_exp_f32_e32 v197, v97
	v_exp_f32_e32 v193, v98
	v_exp_f32_e32 v195, v99
	v_exp_f32_e32 v191, v100
	v_exp_f32_e32 v194, v101
	v_exp_f32_e32 v190, v102
	v_exp_f32_e32 v192, v103
	v_exp_f32_e32 v169, v104
	v_exp_f32_e32 v171, v105
	v_exp_f32_e32 v167, v106
	v_exp_f32_e32 v170, v107
	v_exp_f32_e32 v165, v108
	v_exp_f32_e32 v168, v109
	v_exp_f32_e32 v164, v110
	v_exp_f32_e32 v166, v111
	s_waitcnt lgkmcnt(3)
	v_mfma_f32_32x32x16_bf16 v[96:111], v[80:83], v[136:139], 0
	v_exp_f32_e32 v238, v64
	v_add_f32_e32 v64, v197, v196
	v_add_f32_e32 v64, v193, v64
	v_add_f32_e32 v64, v195, v64
	s_waitcnt lgkmcnt(2)
	v_mfma_f32_32x32x16_bf16 v[80:95], v[84:87], v[136:139], 0
	v_add_f32_e32 v64, v191, v64
	v_add_f32_e32 v64, v194, v64
	v_add_f32_e32 v64, v190, v64
	v_add_f32_e32 v64, v192, v64
	v_add_f32_e32 v64, v169, v64
	v_add_f32_e32 v64, v171, v64
	s_waitcnt lgkmcnt(1)
	v_mfma_f32_32x32x16_bf16 v[96:111], v[198:201], v[140:143], v[96:111]
	v_add_f32_e32 v64, v167, v64
	v_add_f32_e32 v64, v170, v64
	v_add_f32_e32 v64, v165, v64
	v_add_f32_e32 v64, v168, v64
	v_add_f32_e32 v64, v164, v64
	v_add_f32_e32 v64, v166, v64
	v_exp_f32_e32 v239, v68
	s_waitcnt lgkmcnt(0)
	v_mfma_f32_32x32x16_bf16 v[80:95], v[202:205], v[140:143], v[80:95]
	ds_read_b128 v[198:201], v180 offset:49152
	ds_read_b128 v[202:205], v180 offset:57344
	v_add_f32_e32 v64, v238, v64
	v_exp_f32_e32 v240, v69
	v_exp_f32_e32 v241, v70
	v_exp_f32_e32 v242, v71
	s_waitcnt lgkmcnt(1)
	v_mfma_f32_32x32x16_bf16 v[96:111], v[198:201], v[132:135], v[96:111]
	ds_read_b128 v[198:201], v181 offset:49152
	ds_read_b128 v[206:209], v181 offset:57344
	ds_read_b128 v[210:213], v182 offset:49152
	ds_read_b128 v[214:217], v182 offset:57344
	ds_read_b128 v[218:221], v183 offset:49152
	ds_read_b128 v[222:225], v183 offset:57344
	v_exp_f32_e32 v243, v76
	v_exp_f32_e32 v244, v77
	v_exp_f32_e32 v245, v78
	v_exp_f32_e32 v79, v79
	s_waitcnt lgkmcnt(6)
	v_mfma_f32_32x32x16_bf16 v[80:95], v[202:205], v[132:135], v[80:95]
	ds_read_b128 v[202:205], v184 offset:49152
	ds_read_b128 v[226:229], v184 offset:57344
	ds_read_b128 v[230:233], v185 offset:49152
	ds_read_b128 v[234:237], v185 offset:57344
	s_waitcnt lgkmcnt(9)
	v_mfma_f32_32x32x16_bf16 v[96:111], v[198:201], v[128:131], v[96:111]
	v_exp_f32_e32 v199, v65
	v_exp_f32_e32 v200, v66
	v_exp_f32_e32 v201, v67
	v_add_f32_e32 v64, v199, v64
	v_add_f32_e32 v64, v200, v64
	v_add_f32_e32 v64, v201, v64
	s_waitcnt lgkmcnt(8)
	v_mfma_f32_32x32x16_bf16 v[80:95], v[206:209], v[128:131], v[80:95]
	v_exp_f32_e32 v206, v72
	v_add_f32_e32 v64, v239, v64
	v_exp_f32_e32 v207, v73
	v_add_f32_e32 v64, v240, v64
	v_exp_f32_e32 v208, v74
	v_add_f32_e32 v64, v241, v64
	v_exp_f32_e32 v209, v75
	s_waitcnt lgkmcnt(7)
	v_mfma_f32_32x32x16_bf16 v[96:111], v[210:213], v[124:127], v[96:111]
	v_add_f32_e32 v64, v242, v64
	v_add_f32_e32 v64, v206, v64
	v_add_f32_e32 v64, v207, v64
	v_add_f32_e32 v64, v208, v64
	v_add_f32_e32 v64, v209, v64
	v_add_f32_e32 v64, v243, v64
	v_add_f32_e32 v64, v244, v64
	s_waitcnt lgkmcnt(6)
	v_mfma_f32_32x32x16_bf16 v[80:95], v[214:217], v[124:127], v[80:95]
	v_add_f32_e32 v64, v245, v64
	v_add_f32_e32 v198, v79, v64
	v_cvt_pk_bf16_f32 v64, v196, v197
	v_cvt_pk_bf16_f32 v65, v193, v195
	v_cvt_pk_bf16_f32 v66, v191, v194
	v_cvt_pk_bf16_f32 v67, v190, v192
	s_waitcnt lgkmcnt(5)
	v_mfma_f32_32x32x16_bf16 v[96:111], v[218:221], v[120:123], v[96:111]
	v_cvt_pk_bf16_f32 v68, v169, v171
	v_cvt_pk_bf16_f32 v69, v167, v170
	v_cvt_pk_bf16_f32 v70, v165, v168
	v_cvt_pk_bf16_f32 v71, v164, v166
	v_cvt_pk_bf16_f32 v72, v238, v199
	v_cvt_pk_bf16_f32 v73, v200, v201
	v_cvt_pk_bf16_f32 v74, v239, v240
	s_waitcnt lgkmcnt(4)
	v_mfma_f32_32x32x16_bf16 v[80:95], v[222:225], v[120:123], v[80:95]
	v_cvt_pk_bf16_f32 v75, v241, v242
	v_cvt_pk_bf16_f32 v76, v206, v207
	v_cvt_pk_bf16_f32 v77, v208, v209
	v_cvt_pk_bf16_f32 v78, v243, v244
	v_cvt_pk_bf16_f32 v79, v245, v79
	s_waitcnt lgkmcnt(3)
	v_mfma_f32_32x32x16_bf16 v[96:111], v[202:205], v[116:119], v[96:111]
	s_add_i32 s33, s40, 0x8000
	s_and_b32 s43, s33, 0xc000
	ds_read_b64_tr_b16 v[190:191], v176 offset:32768
	ds_read_b64_tr_b16 v[192:193], v176 offset:34816
	ds_read_b64_tr_b16 v[194:195], v176 offset:36864
	ds_read_b64_tr_b16 v[196:197], v176 offset:38912
	s_waitcnt lgkmcnt(6)
	v_mfma_f32_32x32x16_bf16 v[80:95], v[226:229], v[116:119], v[80:95]
	ds_read_b64_tr_b16 v[200:201], v176 offset:40960
	ds_read_b64_tr_b16 v[202:203], v176 offset:43008
	ds_read_b64_tr_b16 v[204:205], v176 offset:45056
	ds_read_b64_tr_b16 v[206:207], v176 offset:47104
	s_add_i32 s73, s40, 0x4000
	s_and_b32 s73, s73, 0xc000
	s_add_u32 s98, s38, s22
	s_addc_u32 s99, s39, s23
	s_add_i32 s41, s66, s73
	s_add_u32 s100, s38, s24
	s_addc_u32 s101, s39, s25
	s_mov_b32 m0, s41
	s_add_i32 s73, s67, s73
	global_load_lds_dwordx4 v156, s[98:99]
	s_waitcnt lgkmcnt(9)
; #define SBAR() __builtin_amdgcn_sched_barrier(0)
; #define PUBLISH(n) do { asm volatile("s_waitcnt vmcnt(" #n ")" ::: "memory"); asm volatile("s_waitcnt lgkmcnt(0)" ::: "memory"); __builtin_amdgcn_s_barrier(); SBAR(); } while (0)
; template <int D0> __device__ __forceinline__ void pv_one(f32x16& od, int vb, bf16x8 pa0, bf16x8 pa1, bf16x8 pa2, bf16x8 pa3) {
;   const s16x4 l0 = tr_read<v_rd_off(D0, 0, 0)>(vb), h0 = tr_read<v_rd_off(D0, 0, 1)>(vb), l1 = tr_read<v_rd_off(D0, 1, 0)>(vb), h1 = tr_read<v_rd_off(D0, 1, 1)>(vb);
;   const s16x4 l2 = tr_read<v_rd_off(D0, 2, 0)>(vb), h2 = tr_read<v_rd_off(D0, 2, 1)>(vb), l3 = tr_read<v_rd_off(D0, 3, 0)>(vb), h3 = tr_read<v_rd_off(D0, 3, 1)>(vb);
;   asm volatile("s_waitcnt lgkmcnt(0)" ::: "memory"); SBAR();
;     ...
;   od = __builtin_amdgcn_mfma_f32_32x32x16_bf16(pa0, PK(l0, h0), od, 0, 0, 0);
;   od = __builtin_amdgcn_mfma_f32_32x32x16_bf16(pa1, PK(l1, h1), od, 0, 0, 0);
;   od = __builtin_amdgcn_mfma_f32_32x32x16_bf16(pa2, PK(l2, h2), od, 0, 0, 0);
;   od = __builtin_amdgcn_mfma_f32_32x32x16_bf16(pa3, PK(l3, h3), od, 0, 0, 0);
;     ...
; }
; __device__ __forceinline__ void pv_d0(f32x16* o, int vb, bf16x8 pa0, bf16x8 pa1, bf16x8 pa2, bf16x8 pa3) {
;   pv_one<0>(o[0], vb, pa0, pa1, pa2, pa3); pv_one<1>(o[1], vb, pa0, pa1, pa2, pa3); pv_one<2>(o[2], vb, pa0, pa1, pa2, pa3); pv_one<3>(o[3], vb, pa0, pa1, pa2, pa3);
; }
; template <typename TQ> ...
;     ...
;   for (int j = 1; j + 1 < NT; j += 2) {
;     SBAR(); qkt(pB0, pB1, (const bf16*)(K_lds + (j & 3) * (int)SHM_K), qr, r32, hi);
;     finishSM(pA0, pA1, alA, l_reg, pa0, pa1, pa2, pa3); SBAR();
;     DMA_TILE(j + 2, (j + 2) & 3); SBAR();
;     pv_d0(o, vb0 + ((j - 1) & 3) * (int)SHM_V, pa0, pa1, pa2, pa3); partialSM<true>(pB0, pB1, m_reg, mnB, alB);
;     PUBLISH(4);
;     SBAR(); qkt(pA0, pA1, (const bf16*)(K_lds + ((j + 1) & 3) * (int)SHM_K), qr, r32, hi);
;     finishSM(pB0, pB1, alB, l_reg, pa0, pa1, pa2, pa3); SBAR();
;     if (j + 3 < NT) { DMA_TILE(j + 3, (j + 3) & 3); } SBAR();
;     pv_d0(o, vb0 + (j & 3) * (int)SHM_V, pa0, pa1, pa2, pa3); partialSM<true>(pA0, pA1, m_reg, mnA, alA);
;     if (j + 3 < NT) { PUBLISH(4); } else { PUBLISH(0); }
;   }
	v_mfma_f32_32x32x16_bf16 v[96:111], v[230:233], v[112:115], v[96:111]
	s_add_i32 m0, s41, 0x2000
	s_nop 0
	global_load_lds_dwordx4 v158, s[98:99]
	s_mov_b32 m0, s73
	s_nop 0
	global_load_lds_dwordx4 v162, s[100:101]
	s_waitcnt lgkmcnt(8)
	v_mfma_f32_32x32x16_bf16 v[80:95], v[234:237], v[112:115], v[80:95]
	s_add_i32 m0, s73, 0x2000
	s_nop 0
	global_load_lds_dwordx4 v160, s[100:101]
	s_nop 0
	s_waitcnt lgkmcnt(6)
	v_mfma_f32_32x32x16_bf16 v[48:63], v[64:67], v[190:193], v[48:63]
	v_exp_f32_e32 v232, v96
	ds_read_b64_tr_b16 v[190:191], v176 offset:33280
	ds_read_b64_tr_b16 v[192:193], v176 offset:35328
	s_waitcnt lgkmcnt(6)
	v_mfma_f32_32x32x16_bf16 v[48:63], v[68:71], v[194:197], v[48:63]
	v_exp_f32_e32 v233, v97
	ds_read_b64_tr_b16 v[194:195], v176 offset:37376
	ds_read_b64_tr_b16 v[196:197], v176 offset:39424
	s_waitcnt lgkmcnt(6)
	v_mfma_f32_32x32x16_bf16 v[48:63], v[72:75], v[200:203], v[48:63]
	v_exp_f32_e32 v234, v98
	ds_read_b64_tr_b16 v[200:201], v176 offset:41472
	ds_read_b64_tr_b16 v[202:203], v176 offset:43520
	ds_read_b64_tr_b16 v[208:209], v176 offset:45568
	ds_read_b64_tr_b16 v[210:211], v176 offset:47616
	s_waitcnt lgkmcnt(8)
	v_mfma_f32_32x32x16_bf16 v[48:63], v[76:79], v[204:207], v[48:63]
	v_exp_f32_e32 v235, v99
	s_waitcnt lgkmcnt(6)
	v_mfma_f32_32x32x16_bf16 v[32:47], v[64:67], v[190:193], v[32:47]
	v_exp_f32_e32 v236, v100
	ds_read_b64_tr_b16 v[190:191], v176 offset:33792
	ds_read_b64_tr_b16 v[192:193], v176 offset:35840
	s_waitcnt lgkmcnt(6)
	v_mfma_f32_32x32x16_bf16 v[32:47], v[68:71], v[194:197], v[32:47]
	v_exp_f32_e32 v237, v101
	ds_read_b64_tr_b16 v[194:195], v176 offset:37888
	ds_read_b64_tr_b16 v[196:197], v176 offset:39936
	s_waitcnt lgkmcnt(6)
	v_mfma_f32_32x32x16_bf16 v[32:47], v[72:75], v[200:203], v[32:47]
	v_exp_f32_e32 v238, v102
	ds_read_b64_tr_b16 v[200:201], v176 offset:41984
	ds_read_b64_tr_b16 v[202:203], v176 offset:44032
	ds_read_b64_tr_b16 v[204:205], v176 offset:46080
	ds_read_b64_tr_b16 v[206:207], v176 offset:48128
	s_waitcnt lgkmcnt(8)
	v_mfma_f32_32x32x16_bf16 v[32:47], v[76:79], v[208:211], v[32:47]
	v_exp_f32_e32 v239, v103
	v_exp_f32_e32 v240, v104
	s_waitcnt lgkmcnt(6)
	v_mfma_f32_32x32x16_bf16 v[16:31], v[64:67], v[190:193], v[16:31]
	v_exp_f32_e32 v241, v105
	ds_read_b64_tr_b16 v[190:191], v176 offset:34304
	ds_read_b64_tr_b16 v[192:193], v176 offset:36352
	s_waitcnt lgkmcnt(6)
	v_mfma_f32_32x32x16_bf16 v[16:31], v[68:71], v[194:197], v[16:31]
	v_exp_f32_e32 v242, v106
	ds_read_b64_tr_b16 v[194:195], v176 offset:38400
	ds_read_b64_tr_b16 v[196:197], v176 offset:40448
	s_waitcnt lgkmcnt(6)
	v_mfma_f32_32x32x16_bf16 v[16:31], v[72:75], v[200:203], v[16:31]
	v_exp_f32_e32 v243, v107
	ds_read_b64_tr_b16 v[200:201], v176 offset:42496
	ds_read_b64_tr_b16 v[202:203], v176 offset:44544
	ds_read_b64_tr_b16 v[208:209], v176 offset:46592
	ds_read_b64_tr_b16 v[210:211], v176 offset:48640
	s_waitcnt lgkmcnt(8)
	v_mfma_f32_32x32x16_bf16 v[16:31], v[76:79], v[204:207], v[16:31]
	v_exp_f32_e32 v244, v108
	s_waitcnt lgkmcnt(6)
	v_mfma_f32_32x32x16_bf16 v[0:15], v[64:67], v[190:193], v[0:15]
	v_exp_f32_e32 v245, v109
	s_waitcnt lgkmcnt(4)
	v_mfma_f32_32x32x16_bf16 v[0:15], v[68:71], v[194:197], v[0:15]
	v_exp_f32_e32 v246, v110
	s_waitcnt lgkmcnt(2)
	v_mfma_f32_32x32x16_bf16 v[0:15], v[72:75], v[200:203], v[0:15]
	v_exp_f32_e32 v247, v111
	s_waitcnt vmcnt(4)
	s_waitcnt lgkmcnt(0)
	s_barrier
	v_mfma_f32_32x32x16_bf16 v[0:15], v[76:79], v[208:211], v[0:15]
	s_and_b32 s40, s40, 0xc000
	s_add_i32 s40, s56, s40
	ds_read_b128 v[64:67], v178
	ds_read_b128 v[68:71], v178 offset:8192
	ds_read_b128 v[190:193], v179
	ds_read_b128 v[194:197], v179 offset:8192
	v_exp_f32_e32 v80, v80
	v_exp_f32_e32 v81, v81
	v_exp_f32_e32 v82, v82
	v_exp_f32_e32 v83, v83
	v_exp_f32_e32 v87, v87
	v_exp_f32_e32 v248, v93
	v_exp_f32_e32 v249, v94
	s_waitcnt lgkmcnt(3)
	v_mfma_f32_32x32x16_bf16 v[96:111], v[64:67], v[136:139], 0
	s_waitcnt lgkmcnt(2)
	v_mfma_f32_32x32x16_bf16 v[64:79], v[68:71], v[136:139], 0
	s_waitcnt lgkmcnt(1)
	v_mfma_f32_32x32x16_bf16 v[96:111], v[190:193], v[140:143], v[96:111]
	s_waitcnt lgkmcnt(0)
	v_mfma_f32_32x32x16_bf16 v[64:79], v[194:197], v[140:143], v[64:79]
	ds_read_b128 v[190:193], v180
	ds_read_b128 v[194:197], v180 offset:8192
	s_waitcnt lgkmcnt(1)
	v_mfma_f32_32x32x16_bf16 v[96:111], v[190:193], v[132:135], v[96:111]
	ds_read_b128 v[190:193], v181
	ds_read_b128 v[200:203], v181 offset:8192
	ds_read_b128 v[204:207], v182
	ds_read_b128 v[208:211], v182 offset:8192
	ds_read_b128 v[212:215], v183
	ds_read_b128 v[216:219], v183 offset:8192
	s_waitcnt lgkmcnt(6)
	v_mfma_f32_32x32x16_bf16 v[64:79], v[194:197], v[132:135], v[64:79]
	ds_read_b128 v[194:197], v184
	ds_read_b128 v[220:223], v184 offset:8192
	ds_read_b128 v[224:227], v185
	ds_read_b128 v[228:231], v185 offset:8192
	s_waitcnt lgkmcnt(9)
	v_mfma_f32_32x32x16_bf16 v[96:111], v[190:193], v[128:131], v[96:111]
	s_cmp_ge_u32 s72, s37
	s_cselect_b64 s[40:41], -1, 0
	s_and_b64 vcc, exec, s[40:41]
	s_cbranch_vccnz .Lat1367_b

; #define SBAR() __builtin_amdgcn_sched_barrier(0)
; template <typename TQ> ...
;     ...
;     if (j + 3 < NT) { DMA_TILE(j + 3, (j + 3) & 3); } SBAR();
	s_add_i32 s73, s66, s43
	s_add_u32 s98, s38, s26
	s_addc_u32 s99, s39, s27
	s_mov_b32 m0, s73
	s_add_i32 s43, s67, s43
	global_load_lds_dwordx4 v156, s[98:99]
	s_add_u32 s100, s38, s28
	s_addc_u32 s101, s39, s29
	s_add_i32 m0, s73, 0x2000
	s_nop 0
	global_load_lds_dwordx4 v158, s[98:99]
	s_mov_b32 m0, s43
	s_nop 0
	global_load_lds_dwordx4 v162, s[100:101]
	s_add_i32 m0, s43, 0x2000
	s_nop 0
	global_load_lds_dwordx4 v160, s[100:101]
